# v102 + gemm_in norm-weight pointer fetched by s_load (no dependent global load / vmcnt(0))
# speedup vs baseline: 1.0063x; 1.0063x over previous
.LBB0_387:
	s_or_b64 exec, exec, s[22:23]
	s_or_b64 s[40:41], s[8:9], s[18:19]
	s_or_b64 s[0:1], s[40:41], s[10:11]
	s_or_b64 s[42:43], s[0:1], s[20:21]
	s_and_saveexec_b64 s[0:1], s[42:43]
	s_cbranch_execz .LBB0_389
	v_cndmask_b32_e64 v0, 23, 22, s[10:11]
	v_cndmask_b32_e64 v0, v0, 20, s[18:19]
	v_cndmask_b32_e64 v0, v0, 19, s[8:9]
	v_readlane_b32 s22, v249, 1
	v_lshlrev_b32_e32 v0, 3, v0
	v_readlane_b32 s23, v249, 2
	v_lshlrev_b32_e32 v2, 2, v166
	v_mov_b32_e32 v3, v153
	v_readfirstlane_b32 s100, v0
	s_nop 3
	s_load_dwordx2 s[100:101], s[22:23], s100
	s_waitcnt lgkmcnt(0)
	v_mov_b32_e32 v0, s100
	v_mov_b32_e32 v1, s101
	v_lshl_add_u64 v[0:1], s[34:35], 2, v[0:1]
	v_lshl_add_u64 v[12:13], v[0:1], 0, v[2:3]
	global_load_dwordx4 v[0:3], v[12:13], off
	global_load_dwordx4 v[4:7], v[12:13], off offset:64
	global_load_dwordx4 v[8:11], v[12:13], off offset:128
	s_nop 0
	global_load_dwordx4 v[12:15], v[12:13], off offset:192
